# K-loop: mid-segment priority dips removed (32 MFMAs at priority 1 without interruption)
# baseline (speedup 1.0000x reference)
; #define PG8_LDA(dst, b, h) do { _Pragma("unroll") for (int m = 0; m < 4; ++m) _Pragma("unroll") for (int k = 0; k < 2; ++k) dst[m][k] = *(const LAS bf16x8*)(lds + PG8_SA(b, h) + aoff + m * 2048 + k * 1024); } while (0)
; #define PG8_LDB(dst, b, h) do { _Pragma("unroll") for (int n = 0; n < 2; ++n) _Pragma("unroll") for (int k = 0; k < 2; ++k) dst[n][k] = *(const LAS bf16x8*)(lds + PG8_SB(b, h) + boff + n * 2048 + k * 1024); } while (0)
; #define PG8_MMA(ai, bj, At, Bt) do { __builtin_amdgcn_s_setprio(1); _Pragma("unroll") for (int m = 0; m < 4; ++m) _Pragma("unroll") for (int n = 0; n < 2; ++n) _Pragma("unroll") for (int k = 0; k < 2; ++k) \
;         acc[ai][bj][m][n] = __builtin_amdgcn_mfma_f32_16x16x32_bf16(Bt[n][k], At[m][k], acc[ai][bj][m][n], 0, 0, 0); __builtin_amdgcn_s_setprio(0); } while (0)
; #define PG8_WAIT_V(n) asm volatile("s_waitcnt vmcnt(" #n ")" ::: "memory")
; #define PG8_WAIT_L(n) asm volatile("s_waitcnt lgkmcnt(" #n ")" ::: "memory")
; #define PG8_BAR __builtin_amdgcn_s_barrier()
; #define PG8_SCHED __builtin_amdgcn_sched_barrier(0)
; #define PG8_STA(bufoff, gbase, ld) PG8_STAGE(bufoff, gbase, RA0 * (unsigned)(ld) + CC0, RA1 * (unsigned)(ld) + CC1)
; #define PG8_STB(bufoff, gbase, ld) PG8_STAGE(bufoff, gbase, RB0 * (unsigned)(ld) + CC0, RB1 * (unsigned)(ld) + CC1)
; __device__ __forceinline__ void gemm_phase(LAS unsigned char* lds, const Sched& S, const Epi& E) {
;     ...
;             PG8_LDB(B0, 0, 0); PG8_LDB(B1, 0, 1); PG8_SCHED; PG8_LDA(At, 0, 0); PG8_STA(PG8_SA(1, 1), a1 + hA, lda);
;             PG8_WAIT_V(8); PG8_WAIT_L(0); PG8_BAR; PG8_MMA(0, 0, At, B0); PG8_MMA(0, 1, At, B1); PG8_BAR; PG8_SCHED;
;             PG8_LDA(At, 0, 1); PG8_STB(PG8_SB(0, 0), b2, xldb); PG8_STB(PG8_SB(0, 1), b2 + xhB, xldb); PG8_STA(PG8_SA(0, 0), a2, xlda);
;             PG8_WAIT_V(8); PG8_WAIT_L(0); PG8_BAR; PG8_MMA(1, 0, At, B0); PG8_MMA(1, 1, At, B1); PG8_BAR; PG8_SCHED;
.LBB0_263:
	s_add_i32 s24, s8, 2
	s_add_u32 s26, vcc_lo, 0x80
	s_addc_u32 s9, vcc_hi, 0
	s_add_i32 s37, 0, 0x10000
	s_cmp_eq_u32 s21, s8
	s_cselect_b32 s9, s7, s9
	s_cselect_b32 s8, s6, s26
	s_cselect_b32 s92, s11, s61
	s_cselect_b32 s30, s22, s20
	v_add_u32_e32 v0, s37, v241
	s_cselect_b32 s29, s13, s72
	s_cselect_b32 s28, s12, s2
	s_add_i32 s57, 0, 0x14000
	ds_read_b128 v[134:137], v0
	ds_read_b128 v[138:141], v0 offset:1024
	ds_read_b128 v[142:145], v0 offset:2048
	ds_read_b128 v[146:149], v0 offset:3072
	v_add_u32_e32 v0, s57, v241
	ds_read_b128 v[150:153], v0
	ds_read_b128 v[154:157], v0 offset:1024
	ds_read_b128 v[158:161], v0 offset:2048
	ds_read_b128 v[162:165], v0 offset:3072
	s_mov_b32 s93, s31
	s_lshl_b64 s[26:27], s[30:31], 8
	v_add_u32_e32 v0, 0, v240
	v_lshl_add_u64 v[214:215], vcc, 0, v[130:131]
	s_add_i32 m0, s34, 0xc000
	ds_read_b128 v[166:169], v0
	ds_read_b128 v[170:173], v0 offset:1024
	ds_read_b128 v[174:177], v0 offset:2048
	ds_read_b128 v[178:181], v0 offset:3072
	ds_read_b128 v[182:185], v0 offset:4096
	ds_read_b128 v[186:189], v0 offset:5120
	ds_read_b128 v[190:193], v0 offset:6144
	ds_read_b128 v[210:213], v0 offset:7168
	global_load_lds_dwordx4 v[214:215], off
	v_lshl_add_u64 v[214:215], vcc, 0, v[132:133]
	s_add_i32 m0, s34, 0xe000
	s_nop 0
	global_load_lds_dwordx4 v[214:215], off
	s_waitcnt vmcnt(8)
	s_waitcnt lgkmcnt(0)
	s_barrier
	s_setprio 1
	s_waitcnt lgkmcnt(0)
	v_mfma_f32_16x16x32_bf16 v[126:129], v[134:137], v[166:169], v[126:129]
	v_mfma_f32_16x16x32_bf16 v[122:125], v[142:145], v[166:169], v[122:125]
	v_mfma_f32_16x16x32_bf16 v[110:113], v[134:137], v[174:177], v[110:113]
	v_mfma_f32_16x16x32_bf16 v[106:109], v[142:145], v[174:177], v[106:109]
	v_mfma_f32_16x16x32_bf16 v[98:101], v[134:137], v[182:185], v[98:101]
	v_mfma_f32_16x16x32_bf16 v[90:93], v[142:145], v[182:185], v[90:93]
	v_mfma_f32_16x16x32_bf16 v[82:85], v[134:137], v[190:193], v[82:85]
	v_mfma_f32_16x16x32_bf16 v[74:77], v[142:145], v[190:193], v[74:77]
	v_mfma_f32_16x16x32_bf16 v[126:129], v[138:141], v[170:173], v[126:129]
	v_mfma_f32_16x16x32_bf16 v[122:125], v[146:149], v[170:173], v[122:125]
	v_mfma_f32_16x16x32_bf16 v[110:113], v[138:141], v[178:181], v[110:113]
	v_mfma_f32_16x16x32_bf16 v[106:109], v[146:149], v[178:181], v[106:109]
	v_mfma_f32_16x16x32_bf16 v[98:101], v[138:141], v[186:189], v[98:101]
	v_mfma_f32_16x16x32_bf16 v[90:93], v[146:149], v[186:189], v[90:93]
	v_mfma_f32_16x16x32_bf16 v[82:85], v[138:141], v[210:213], v[82:85]
	v_mfma_f32_16x16x32_bf16 v[74:77], v[146:149], v[210:213], v[74:77]
	v_mfma_f32_16x16x32_bf16 v[118:121], v[150:153], v[166:169], v[118:121]
	v_mfma_f32_16x16x32_bf16 v[114:117], v[158:161], v[166:169], v[114:117]
	v_mfma_f32_16x16x32_bf16 v[102:105], v[150:153], v[174:177], v[102:105]
	v_mfma_f32_16x16x32_bf16 v[94:97], v[158:161], v[174:177], v[94:97]
	v_mfma_f32_16x16x32_bf16 v[86:89], v[150:153], v[182:185], v[86:89]
	v_mfma_f32_16x16x32_bf16 v[78:81], v[158:161], v[182:185], v[78:81]
	v_mfma_f32_16x16x32_bf16 v[70:73], v[150:153], v[190:193], v[70:73]
	v_mfma_f32_16x16x32_bf16 v[66:69], v[158:161], v[190:193], v[66:69]
	v_mfma_f32_16x16x32_bf16 v[118:121], v[154:157], v[170:173], v[118:121]
	v_mfma_f32_16x16x32_bf16 v[114:117], v[162:165], v[170:173], v[114:117]
	v_mfma_f32_16x16x32_bf16 v[102:105], v[154:157], v[178:181], v[102:105]
	v_mfma_f32_16x16x32_bf16 v[94:97], v[162:165], v[178:181], v[94:97]
	v_mfma_f32_16x16x32_bf16 v[86:89], v[154:157], v[186:189], v[86:89]
	v_mfma_f32_16x16x32_bf16 v[78:81], v[162:165], v[186:189], v[78:81]
	v_mfma_f32_16x16x32_bf16 v[70:73], v[154:157], v[210:213], v[70:73]
	v_mfma_f32_16x16x32_bf16 v[66:69], v[162:165], v[210:213], v[66:69]
	s_setprio 0
	s_barrier
	s_add_i32 s37, s37, s25
	v_mad_u64_u32 v[214:215], s[80:81], s92, v237, v[194:195]
	s_mov_b32 m0, s37
	ds_read_b128 v[166:169], v0 offset:16384
	ds_read_b128 v[170:173], v0 offset:17408
	ds_read_b128 v[174:177], v0 offset:18432
	ds_read_b128 v[178:181], v0 offset:19456
	ds_read_b128 v[182:185], v0 offset:20480
	ds_read_b128 v[186:189], v0 offset:21504
	ds_read_b128 v[190:193], v0 offset:22528
	ds_read_b128 v[210:213], v0 offset:23552
	s_lshl_b64 s[74:75], s[92:93], 8
	global_load_lds_dwordx4 v214, s[28:29]
	s_add_i32 m0, s37, 0x2000
	s_add_u32 s74, s28, s74
	v_mad_u64_u32 v[216:217], s[80:81], s92, v238, v[196:197]
	s_addc_u32 s75, s29, s75
	s_add_i32 s37, s57, s25
	global_load_lds_dwordx4 v216, s[28:29]
	s_mov_b32 m0, s37
	v_mad_u64_u32 v[218:219], s[80:81], s30, v235, v[194:195]
	global_load_lds_dwordx4 v214, s[74:75]
	s_add_i32 m0, s37, 0x2000
	v_mad_u64_u32 v[220:221], s[80:81], s30, v236, v[196:197]
	global_load_lds_dwordx4 v216, s[74:75]
	s_mov_b32 m0, s34
	v_mov_b32_e32 v215, v1
	global_load_lds_dwordx4 v218, s[8:9]
	s_mov_b32 m0, s35
	v_mov_b32_e32 v217, v1
	global_load_lds_dwordx4 v220, s[8:9]
	v_mov_b32_e32 v219, v1
	v_mov_b32_e32 v221, v1
	v_lshl_add_u64 v[222:223], s[28:29], 0, v[214:215]
	v_lshl_add_u64 v[224:225], s[28:29], 0, v[216:217]
	v_lshl_add_u64 v[214:215], s[74:75], 0, v[214:215]
	v_lshl_add_u64 v[216:217], s[74:75], 0, v[216:217]
	v_lshl_add_u64 v[226:227], s[8:9], 0, v[218:219]
	v_lshl_add_u64 v[228:229], s[8:9], 0, v[220:221]
	s_waitcnt vmcnt(8)
	s_waitcnt lgkmcnt(0)
	s_barrier
; #define PG8_LDA(dst, b, h) do { _Pragma("unroll") for (int m = 0; m < 4; ++m) _Pragma("unroll") for (int k = 0; k < 2; ++k) dst[m][k] = *(const LAS bf16x8*)(lds + PG8_SA(b, h) + aoff + m * 2048 + k * 1024); } while (0)
; #define PG8_LDB(dst, b, h) do { _Pragma("unroll") for (int n = 0; n < 2; ++n) _Pragma("unroll") for (int k = 0; k < 2; ++k) dst[n][k] = *(const LAS bf16x8*)(lds + PG8_SB(b, h) + boff + n * 2048 + k * 1024); } while (0)
; #define PG8_MMA(ai, bj, At, Bt) do { __builtin_amdgcn_s_setprio(1); _Pragma("unroll") for (int m = 0; m < 4; ++m) _Pragma("unroll") for (int n = 0; n < 2; ++n) _Pragma("unroll") for (int k = 0; k < 2; ++k) \
;         acc[ai][bj][m][n] = __builtin_amdgcn_mfma_f32_16x16x32_bf16(Bt[n][k], At[m][k], acc[ai][bj][m][n], 0, 0, 0); __builtin_amdgcn_s_setprio(0); } while (0)
; #define PG8_WAIT_V(n) asm volatile("s_waitcnt vmcnt(" #n ")" ::: "memory")
; #define PG8_WAIT_L(n) asm volatile("s_waitcnt lgkmcnt(" #n ")" ::: "memory")
; #define PG8_BAR __builtin_amdgcn_s_barrier()
; #define PG8_SCHED __builtin_amdgcn_sched_barrier(0)
; #define PG8_STA(bufoff, gbase, ld) PG8_STAGE(bufoff, gbase, RA0 * (unsigned)(ld) + CC0, RA1 * (unsigned)(ld) + CC1)
; __device__ __forceinline__ void gemm_phase(LAS unsigned char* lds, const Sched& S, const Epi& E) {
;     ...
;             PG8_WAIT_V(8); PG8_WAIT_L(0); PG8_BAR; PG8_MMA(1, 0, At, B0); PG8_MMA(1, 1, At, B1); PG8_BAR; PG8_SCHED;
;             PG8_LDB(B0, 1, 0); PG8_LDB(B1, 1, 1); PG8_SCHED; PG8_LDA(At, 1, 0); PG8_STA(PG8_SA(0, 1), a2 + xhA, xlda);
;             PG8_WAIT_V(8); PG8_WAIT_L(0); PG8_BAR; PG8_MMA(0, 0, At, B0); PG8_MMA(0, 1, At, B1); PG8_BAR; PG8_SCHED;
	s_setprio 1
	s_waitcnt lgkmcnt(0)
	v_mfma_f32_16x16x32_bf16 v[62:65], v[134:137], v[166:169], v[62:65]
	v_mfma_f32_16x16x32_bf16 v[58:61], v[142:145], v[166:169], v[58:61]
	v_mfma_f32_16x16x32_bf16 v[46:49], v[134:137], v[174:177], v[46:49]
	v_mfma_f32_16x16x32_bf16 v[42:45], v[142:145], v[174:177], v[42:45]
	v_mfma_f32_16x16x32_bf16 v[30:33], v[134:137], v[182:185], v[30:33]
	v_mfma_f32_16x16x32_bf16 v[26:29], v[142:145], v[182:185], v[26:29]
	v_mfma_f32_16x16x32_bf16 v[14:17], v[134:137], v[190:193], v[14:17]
	v_mfma_f32_16x16x32_bf16 v[10:13], v[142:145], v[190:193], v[10:13]
	v_mfma_f32_16x16x32_bf16 v[62:65], v[138:141], v[170:173], v[62:65]
	v_mfma_f32_16x16x32_bf16 v[58:61], v[146:149], v[170:173], v[58:61]
	v_mfma_f32_16x16x32_bf16 v[46:49], v[138:141], v[178:181], v[46:49]
	v_mfma_f32_16x16x32_bf16 v[42:45], v[146:149], v[178:181], v[42:45]
	v_mfma_f32_16x16x32_bf16 v[30:33], v[138:141], v[186:189], v[30:33]
	v_mfma_f32_16x16x32_bf16 v[26:29], v[146:149], v[186:189], v[26:29]
	v_mfma_f32_16x16x32_bf16 v[14:17], v[138:141], v[210:213], v[14:17]
	v_mfma_f32_16x16x32_bf16 v[10:13], v[146:149], v[210:213], v[10:13]
	v_mfma_f32_16x16x32_bf16 v[54:57], v[150:153], v[166:169], v[54:57]
	v_mfma_f32_16x16x32_bf16 v[50:53], v[158:161], v[166:169], v[50:53]
	v_mfma_f32_16x16x32_bf16 v[38:41], v[150:153], v[174:177], v[38:41]
	v_mfma_f32_16x16x32_bf16 v[34:37], v[158:161], v[174:177], v[34:37]
	v_mfma_f32_16x16x32_bf16 v[22:25], v[150:153], v[182:185], v[22:25]
	v_mfma_f32_16x16x32_bf16 v[18:21], v[158:161], v[182:185], v[18:21]
	v_mfma_f32_16x16x32_bf16 v[6:9], v[150:153], v[190:193], v[6:9]
	v_mfma_f32_16x16x32_bf16 v[2:5], v[158:161], v[190:193], v[2:5]
	v_mfma_f32_16x16x32_bf16 v[54:57], v[154:157], v[170:173], v[54:57]
	v_mfma_f32_16x16x32_bf16 v[50:53], v[162:165], v[170:173], v[50:53]
	v_mfma_f32_16x16x32_bf16 v[38:41], v[154:157], v[178:181], v[38:41]
	v_mfma_f32_16x16x32_bf16 v[34:37], v[162:165], v[178:181], v[34:37]
	v_mfma_f32_16x16x32_bf16 v[22:25], v[154:157], v[186:189], v[22:25]
	v_mfma_f32_16x16x32_bf16 v[18:21], v[162:165], v[186:189], v[18:21]
	v_mfma_f32_16x16x32_bf16 v[6:9], v[154:157], v[210:213], v[6:9]
	v_mfma_f32_16x16x32_bf16 v[2:5], v[162:165], v[210:213], v[2:5]
	s_setprio 0
	s_barrier
	s_add_i32 s28, 0, 0x18000
	s_add_i32 s29, 0, 0x1c000
	v_add_u32_e32 v146, s28, v241
	v_add_u32_e32 v162, s29, v241
	ds_read_b128 v[134:137], v146
	ds_read_b128 v[138:141], v146 offset:1024
	ds_read_b128 v[142:145], v146 offset:2048
	ds_read_b128 v[146:149], v146 offset:3072
	ds_read_b128 v[150:153], v162
	ds_read_b128 v[154:157], v162 offset:1024
	ds_read_b128 v[158:161], v162 offset:2048
	ds_read_b128 v[162:165], v162 offset:3072
	s_add_u32 s8, s8, s26
	s_addc_u32 s9, s9, s27
	s_mov_b32 m0, s39
	ds_read_b128 v[166:169], v0 offset:32768
	ds_read_b128 v[170:173], v0 offset:33792
	ds_read_b128 v[174:177], v0 offset:34816
	ds_read_b128 v[178:181], v0 offset:35840
	ds_read_b128 v[182:185], v0 offset:36864
	ds_read_b128 v[186:189], v0 offset:37888
	ds_read_b128 v[190:193], v0 offset:38912
	ds_read_b128 v[210:213], v0 offset:39936
	global_load_lds_dwordx4 v218, s[8:9]
	s_mov_b32 m0, s91
	s_nop 0
	global_load_lds_dwordx4 v220, s[8:9]
	s_waitcnt vmcnt(8)
	s_waitcnt lgkmcnt(0)
	s_barrier
	s_setprio 1
	s_waitcnt lgkmcnt(0)
	v_mfma_f32_16x16x32_bf16 v[126:129], v[134:137], v[166:169], v[126:129]
	v_mfma_f32_16x16x32_bf16 v[122:125], v[142:145], v[166:169], v[122:125]
	v_mfma_f32_16x16x32_bf16 v[110:113], v[134:137], v[174:177], v[110:113]
	v_mfma_f32_16x16x32_bf16 v[106:109], v[142:145], v[174:177], v[106:109]
	v_mfma_f32_16x16x32_bf16 v[98:101], v[134:137], v[182:185], v[98:101]
	v_mfma_f32_16x16x32_bf16 v[90:93], v[142:145], v[182:185], v[90:93]
	v_mfma_f32_16x16x32_bf16 v[82:85], v[134:137], v[190:193], v[82:85]
	v_mfma_f32_16x16x32_bf16 v[74:77], v[142:145], v[190:193], v[74:77]
	v_mfma_f32_16x16x32_bf16 v[126:129], v[138:141], v[170:173], v[126:129]
	v_mfma_f32_16x16x32_bf16 v[122:125], v[146:149], v[170:173], v[122:125]
	v_mfma_f32_16x16x32_bf16 v[110:113], v[138:141], v[178:181], v[110:113]
	v_mfma_f32_16x16x32_bf16 v[106:109], v[146:149], v[178:181], v[106:109]
	v_mfma_f32_16x16x32_bf16 v[98:101], v[138:141], v[186:189], v[98:101]
	v_mfma_f32_16x16x32_bf16 v[90:93], v[146:149], v[186:189], v[90:93]
	v_mfma_f32_16x16x32_bf16 v[82:85], v[138:141], v[210:213], v[82:85]
	v_mfma_f32_16x16x32_bf16 v[74:77], v[146:149], v[210:213], v[74:77]
	v_mfma_f32_16x16x32_bf16 v[118:121], v[150:153], v[166:169], v[118:121]
	v_mfma_f32_16x16x32_bf16 v[114:117], v[158:161], v[166:169], v[114:117]
	v_mfma_f32_16x16x32_bf16 v[102:105], v[150:153], v[174:177], v[102:105]
	v_mfma_f32_16x16x32_bf16 v[94:97], v[158:161], v[174:177], v[94:97]
	v_mfma_f32_16x16x32_bf16 v[86:89], v[150:153], v[182:185], v[86:89]
	v_mfma_f32_16x16x32_bf16 v[78:81], v[158:161], v[182:185], v[78:81]
	v_mfma_f32_16x16x32_bf16 v[70:73], v[150:153], v[190:193], v[70:73]
	v_mfma_f32_16x16x32_bf16 v[66:69], v[158:161], v[190:193], v[66:69]
	v_mfma_f32_16x16x32_bf16 v[118:121], v[154:157], v[170:173], v[118:121]
	v_mfma_f32_16x16x32_bf16 v[114:117], v[162:165], v[170:173], v[114:117]
	v_mfma_f32_16x16x32_bf16 v[102:105], v[154:157], v[178:181], v[102:105]
	v_mfma_f32_16x16x32_bf16 v[94:97], v[162:165], v[178:181], v[94:97]
	v_mfma_f32_16x16x32_bf16 v[86:89], v[154:157], v[186:189], v[86:89]
	v_mfma_f32_16x16x32_bf16 v[78:81], v[162:165], v[186:189], v[78:81]
	v_mfma_f32_16x16x32_bf16 v[70:73], v[154:157], v[210:213], v[70:73]
	v_mfma_f32_16x16x32_bf16 v[66:69], v[162:165], v[210:213], v[66:69]
	s_setprio 0
	s_barrier
; #define PG8_LDA(dst, b, h) do { _Pragma("unroll") for (int m = 0; m < 4; ++m) _Pragma("unroll") for (int k = 0; k < 2; ++k) dst[m][k] = *(const LAS bf16x8*)(lds + PG8_SA(b, h) + aoff + m * 2048 + k * 1024); } while (0)
; #define PG8_MMA(ai, bj, At, Bt) do { __builtin_amdgcn_s_setprio(1); _Pragma("unroll") for (int m = 0; m < 4; ++m) _Pragma("unroll") for (int n = 0; n < 2; ++n) _Pragma("unroll") for (int k = 0; k < 2; ++k) \
;         acc[ai][bj][m][n] = __builtin_amdgcn_mfma_f32_16x16x32_bf16(Bt[n][k], At[m][k], acc[ai][bj][m][n], 0, 0, 0); __builtin_amdgcn_s_setprio(0); } while (0)
; #define PG8_WAIT_V(n) asm volatile("s_waitcnt vmcnt(" #n ")" ::: "memory")
; #define PG8_WAIT_L(n) asm volatile("s_waitcnt lgkmcnt(" #n ")" ::: "memory")
; #define PG8_BAR __builtin_amdgcn_s_barrier()
; #define PG8_SCHED __builtin_amdgcn_sched_barrier(0)
; #define PG8_STA(bufoff, gbase, ld) PG8_STAGE(bufoff, gbase, RA0 * (unsigned)(ld) + CC0, RA1 * (unsigned)(ld) + CC1)
; #define PG8_STB(bufoff, gbase, ld) PG8_STAGE(bufoff, gbase, RB0 * (unsigned)(ld) + CC0, RB1 * (unsigned)(ld) + CC1)
; __device__ __forceinline__ void gemm_phase(LAS unsigned char* lds, const Sched& S, const Epi& E) {
;     ...
;         for (int t = 0; t < nt_main; t += 2) {
;     ...
;             PG8_LDA(At, 1, 1); PG8_STB(PG8_SB(1, 0), b3, xldb); PG8_STB(PG8_SB(1, 1), b3 + xhB, xldb); PG8_STA(PG8_SA(1, 0), a3, xlda);
;             PG8_WAIT_V(8); PG8_WAIT_L(0); PG8_BAR; PG8_MMA(1, 0, At, B0); PG8_MMA(1, 1, At, B1); PG8_BAR; PG8_SCHED;
	s_add_i32 s8, s28, s25
	v_lshl_add_u64 v[218:219], v[222:223], 0, s[52:53]
	s_mov_b32 m0, s8
	ds_read_b128 v[166:169], v0 offset:49152
	ds_read_b128 v[170:173], v0 offset:50176
	ds_read_b128 v[174:177], v0 offset:51200
	ds_read_b128 v[178:181], v0 offset:52224
	ds_read_b128 v[182:185], v0 offset:53248
	ds_read_b128 v[186:189], v0 offset:54272
	ds_read_b128 v[190:193], v0 offset:55296
	ds_read_b128 v[210:213], v0 offset:56320
	global_load_lds_dwordx4 v[218:219], off
	v_lshl_add_u64 v[218:219], v[224:225], 0, s[52:53]
	s_add_i32 m0, s8, 0x2000
	s_add_i32 s8, s29, s25
	global_load_lds_dwordx4 v[218:219], off
	v_lshl_add_u64 v[214:215], v[214:215], 0, s[52:53]
	s_mov_b32 m0, s8
	s_nop 0
	global_load_lds_dwordx4 v[214:215], off
	v_lshl_add_u64 v[214:215], v[216:217], 0, s[52:53]
	s_add_i32 m0, s8, 0x2000
	s_nop 0
	global_load_lds_dwordx4 v[214:215], off
	v_lshl_add_u64 v[214:215], v[226:227], 0, s[52:53]
	s_mov_b32 m0, s90
	s_nop 0
	global_load_lds_dwordx4 v[214:215], off
	v_lshl_add_u64 v[214:215], v[228:229], 0, s[52:53]
	s_mov_b32 m0, s73
	s_nop 0
	global_load_lds_dwordx4 v[214:215], off
	s_nop 0
	s_waitcnt vmcnt(8)
	s_waitcnt lgkmcnt(0)
	s_barrier
	s_setprio 1
	s_waitcnt lgkmcnt(0)
	v_mfma_f32_16x16x32_bf16 v[62:65], v[134:137], v[166:169], v[62:65]
	v_mfma_f32_16x16x32_bf16 v[58:61], v[142:145], v[166:169], v[58:61]
	v_mfma_f32_16x16x32_bf16 v[46:49], v[134:137], v[174:177], v[46:49]
	v_mfma_f32_16x16x32_bf16 v[42:45], v[142:145], v[174:177], v[42:45]
	v_mfma_f32_16x16x32_bf16 v[30:33], v[134:137], v[182:185], v[30:33]
	v_mfma_f32_16x16x32_bf16 v[26:29], v[142:145], v[182:185], v[26:29]
	v_mfma_f32_16x16x32_bf16 v[14:17], v[134:137], v[190:193], v[14:17]
	v_mfma_f32_16x16x32_bf16 v[10:13], v[142:145], v[190:193], v[10:13]
	v_mfma_f32_16x16x32_bf16 v[62:65], v[138:141], v[170:173], v[62:65]
	v_mfma_f32_16x16x32_bf16 v[58:61], v[146:149], v[170:173], v[58:61]
	v_mfma_f32_16x16x32_bf16 v[46:49], v[138:141], v[178:181], v[46:49]
	v_mfma_f32_16x16x32_bf16 v[42:45], v[146:149], v[178:181], v[42:45]
	v_mfma_f32_16x16x32_bf16 v[30:33], v[138:141], v[186:189], v[30:33]
	v_mfma_f32_16x16x32_bf16 v[26:29], v[146:149], v[186:189], v[26:29]
	v_mfma_f32_16x16x32_bf16 v[14:17], v[138:141], v[210:213], v[14:17]
	v_mfma_f32_16x16x32_bf16 v[10:13], v[146:149], v[210:213], v[10:13]
	v_mfma_f32_16x16x32_bf16 v[54:57], v[150:153], v[166:169], v[54:57]
	v_mfma_f32_16x16x32_bf16 v[50:53], v[158:161], v[166:169], v[50:53]
	v_mfma_f32_16x16x32_bf16 v[38:41], v[150:153], v[174:177], v[38:41]
	v_mfma_f32_16x16x32_bf16 v[34:37], v[158:161], v[174:177], v[34:37]
	v_mfma_f32_16x16x32_bf16 v[22:25], v[150:153], v[182:185], v[22:25]
	v_mfma_f32_16x16x32_bf16 v[18:21], v[158:161], v[182:185], v[18:21]
	v_mfma_f32_16x16x32_bf16 v[6:9], v[150:153], v[190:193], v[6:9]
	v_mfma_f32_16x16x32_bf16 v[2:5], v[158:161], v[190:193], v[2:5]
	v_mfma_f32_16x16x32_bf16 v[54:57], v[154:157], v[170:173], v[54:57]
	v_mfma_f32_16x16x32_bf16 v[50:53], v[162:165], v[170:173], v[50:53]
	v_mfma_f32_16x16x32_bf16 v[38:41], v[154:157], v[178:181], v[38:41]
	v_mfma_f32_16x16x32_bf16 v[34:37], v[162:165], v[178:181], v[34:37]
	v_mfma_f32_16x16x32_bf16 v[22:25], v[154:157], v[186:189], v[22:25]
	v_mfma_f32_16x16x32_bf16 v[18:21], v[162:165], v[186:189], v[18:21]
	v_mfma_f32_16x16x32_bf16 v[6:9], v[154:157], v[210:213], v[6:9]
	v_mfma_f32_16x16x32_bf16 v[2:5], v[162:165], v[210:213], v[2:5]
	s_setprio 0
	s_barrier
	s_add_u32 vcc_lo, vcc_lo, 0x100
	s_addc_u32 vcc_hi, vcc_hi, 0
	s_add_u32 s2, s2, 0x100
	s_addc_u32 s72, s72, 0
	s_cmp_ge_i32 s24, s68
	s_mov_b32 s8, s24
	s_cbranch_scc0 .LBB0_263
	s_nop 0
	s_nop 0
	s_nop 0
	s_nop 0
	s_nop 0
	s_nop 0
	s_nop 0
	s_nop 0
	s_nop 0
	s_mov_b32 s92, s3
	s_movk_i32 s93, 0x3fff
	s_movk_i32 s3, 0x2000
	s_and_b64 vcc, exec, s[44:45]
	s_cbranch_vccz .LBB0_266
